# speedup vs baseline: 1.0171x; 1.0006x over previous
; __device__ __forceinline__ float bflo(unsigned w) { return __uint_as_float(w << 16); }
; __device__ __forceinline__ void norm_rows_b(const bf16_t* hb, int r_begin, int nrows, int stride, int second_off, const float* modl, int shoff, int scoff, bf16_t* xl) {
;     ...
;     for (int r = r_begin; r < nrows; r += stride) {
;         const int r1 = r + second_off; const bool two = r1 < nrows;
;         u32x4 w[2][2]; float s[2];
; #pragma unroll
;         for (int q = 0; q < 2; ++q) { const bf16_t* xr = hb + (size_t)(q ? (two ? r1 : r) : r) * DM + 8 * lane; w[q][0] = *(const u32x4*)(xr); w[q][1] = *(const u32x4*)(xr + 512); }
;         float v[2][16];
; #pragma unroll
;         for (int q = 0; q < 2; ++q) { float a = 0.f;
; #pragma unroll
;             for (int h = 0; h < 2; ++h)
; #pragma unroll
;                 for (int e = 0; e < 4; ++e) { const float lo = bflo(w[q][h][e]), hi = bfhi(w[q][h][e]); v[q][8 * h + 2 * e] = lo; v[q][8 * h + 2 * e + 1] = hi; a += lo * lo + hi * hi; }
;             s[q] = a; }
; #pragma unroll
;         for (int o = 32; o > 0; o >>= 1) { s[0] += __shfl_xor(s[0], o); s[1] += __shfl_xor(s[1], o); }
; #pragma unroll
;         for (int q = 0; q < 2; ++q) { if (q == 1 && !two) break; const int rr = q ? r1 : r; const int cond = rr < MLAT ? (rr >> 13) : 8; const float* mp = modl + cond * 6144;
;             const float rstd = rsqrtf(s[q] * (1.0f / DM) + EPS);
; #pragma unroll
;             for (int h = 0; h < 2; ++h) { const int col = 8 * lane + 512 * h; const f32x4 sc0 = *(const f32x4*)(mp + scoff + col), sc1 = *(const f32x4*)(mp + scoff + col + 4), sh0 = *(const f32x4*)(mp + shoff + col), sh1 = *(const f32x4*)(mp + shoff + col + 4);
;                 u32x4 o;
;                 o.x = cvt_pk_bf16(v[q][8 * h + 0] * rstd * (sc0[0] + 1.0f) + sh0[0], v[q][8 * h + 1] * rstd * (sc0[1] + 1.0f) + sh0[1]);
;                 o.y = cvt_pk_bf16(v[q][8 * h + 2] * rstd * (sc0[2] + 1.0f) + sh0[2], v[q][8 * h + 3] * rstd * (sc0[3] + 1.0f) + sh0[3]);
;                 o.z = cvt_pk_bf16(v[q][8 * h + 4] * rstd * (sc1[0] + 1.0f) + sh1[0], v[q][8 * h + 5] * rstd * (sc1[1] + 1.0f) + sh1[1]);
;                 o.w = cvt_pk_bf16(v[q][8 * h + 6] * rstd * (sc1[2] + 1.0f) + sh1[2], v[q][8 * h + 7] * rstd * (sc1[3] + 1.0f) + sh1[3]);
;                 *(u32x4*)(xl + (size_t)rr * DM + col) = o; } }
.LBB0_335:
	v_ashrrev_i32_e32 v13, 31, v12
	v_lshlrev_b64 v[30:31], 11, v[12:13]
	s_waitcnt lgkmcnt(0)
	v_lshl_add_u64 v[10:11], v[2:3], 0, v[30:31]
	global_load_dwordx4 v[22:25], v[10:11], off
	global_load_dwordx4 v[26:29], v[10:11], off offset:1024
	v_min_i32_e32 v7, 0x10000, v12
	v_add_u32_e32 v10, s42, v12
	v_ashrrev_i32_e32 v7, 13, v7
	v_cmp_gt_i32_e32 vcc, s12, v10
	v_mul_i32_i24_e32 v32, 0x1800, v7
	v_ashrrev_i32_e32 v33, 31, v32
	v_cndmask_b32_e32 v12, v12, v10, vcc
	v_ashrrev_i32_e32 v13, 31, v12
	v_lshl_add_u64 v[48:49], v[32:33], 2, s[54:55]
	v_lshlrev_b64 v[12:13], 11, v[12:13]
	v_lshl_add_u64 v[56:57], v[48:49], 0, s[8:9]
	v_lshl_add_u64 v[12:13], v[2:3], 0, v[12:13]
	v_lshl_add_u64 v[40:41], v[56:57], 0, v[0:1]
	global_load_dwordx4 v[32:35], v[12:13], off
	global_load_dwordx4 v[80:83], v[40:41], off offset:2064
	global_load_dwordx4 v[84:87], v[40:41], off offset:2048
	global_load_dwordx4 v[36:39], v[40:41], off
	s_nop 0
	global_load_dwordx4 v[40:43], v[40:41], off offset:16
	s_nop 0
	global_load_dwordx4 v[44:47], v[12:13], off offset:1024
	v_lshl_add_u64 v[12:13], v[48:49], 0, s[10:11]
	v_lshl_add_u64 v[52:53], v[12:13], 0, v[0:1]
	global_load_dwordx4 v[88:91], v[52:53], off offset:2064
	global_load_dwordx4 v[92:95], v[52:53], off offset:2048
	global_load_dwordx4 v[48:51], v[52:53], off offset:16
	s_nop 0
	global_load_dwordx4 v[52:55], v[52:53], off
	v_lshl_add_u64 v[66:67], v[4:5], 0, v[30:31]
	v_lshl_add_u64 v[12:13], v[12:13], 0, v[8:9]
	s_waitcnt vmcnt(11)
	v_and_b32_e32 v11, 0xffff0000, v22
	v_and_b32_e32 v69, 0xffff0000, v23
	v_lshlrev_b32_e32 v7, 16, v22
	v_lshlrev_b32_e32 v68, 16, v23
	v_and_b32_e32 v71, 0xffff0000, v24
	s_waitcnt vmcnt(10)
	v_lshlrev_b32_e32 v58, 16, v26
	v_and_b32_e32 v60, 0xffff0000, v26
	v_mul_f32_e32 v21, v11, v11
	v_mul_f32_e32 v26, v69, v69
	v_lshlrev_b32_e32 v70, 16, v24
	v_and_b32_e32 v73, 0xffff0000, v25
	v_lshlrev_b32_e32 v59, 16, v27
	v_and_b32_e32 v61, 0xffff0000, v27
	v_mul_f32_e32 v27, v71, v71
	v_fmac_f32_e32 v21, v7, v7
	v_fmac_f32_e32 v26, v68, v68
	v_lshlrev_b32_e32 v72, 16, v25
	v_lshlrev_b32_e32 v62, 16, v28
	v_and_b32_e32 v64, 0xffff0000, v28
	v_mul_f32_e32 v28, v73, v73
	v_fmac_f32_e32 v27, v70, v70
	v_add_f32_e32 v21, v21, v26
	v_pk_mul_f32 v[22:23], v[60:61], v[60:61]
	v_fmac_f32_e32 v28, v72, v72
	v_add_f32_e32 v21, v27, v21
	v_and_b32_e32 v65, 0xffff0000, v29
	v_pk_fma_f32 v[22:23], v[58:59], v[58:59], v[22:23]
	v_add_f32_e32 v21, v28, v21
	v_lshlrev_b32_e32 v63, 16, v29
	v_pk_mul_f32 v[24:25], v[64:65], v[64:65]
	v_add_f32_e32 v21, v22, v21
	v_pk_fma_f32 v[24:25], v[62:63], v[62:63], v[24:25]
	v_add_f32_e32 v21, v23, v21
	v_add_f32_e32 v21, v24, v21
	v_add_f32_e32 v21, v25, v21
	ds_bpermute_b32 v22, v14, v21
	s_waitcnt vmcnt(6)
	v_add_f32_e32 v25, 1.0, v37
	v_lshl_add_u64 v[26:27], v[56:57], 0, v[8:9]
	v_add_f32_e32 v24, 1.0, v36
	v_add_f32_e32 v28, 1.0, v38
	s_waitcnt lgkmcnt(0)
	v_add_f32_e32 v21, v21, v22
	ds_bpermute_b32 v22, v15, v21
	s_waitcnt vmcnt(5)
	v_add_f32_e32 v30, 1.0, v40
	v_add_f32_e32 v29, 1.0, v39
	v_add_f32_e32 v31, 1.0, v42
	v_add_f32_e32 v36, 1.0, v43
	s_waitcnt lgkmcnt(0)
	v_add_f32_e32 v21, v21, v22
	ds_bpermute_b32 v22, v16, v21
	s_waitcnt lgkmcnt(0)
	v_add_f32_e32 v21, v21, v22
	ds_bpermute_b32 v22, v17, v21
	s_waitcnt lgkmcnt(0)
	v_add_f32_e32 v22, v21, v22
	ds_bpermute_b32 v23, v18, v22
	v_lshlrev_b32_e32 v21, 16, v32
	s_waitcnt lgkmcnt(0)
	v_add_f32_e32 v22, v22, v23
	ds_bpermute_b32 v23, v19, v22
	s_waitcnt lgkmcnt(0)
	v_add_f32_e32 v22, v22, v23
	v_fmamk_f32 v22, v22, 0x3a800000, v20
	v_mul_f32_e32 v23, 0x4b800000, v22
	v_cmp_gt_f32_e64 s[6:7], s13, v22
	s_nop 1
	v_cndmask_b32_e64 v22, v22, v23, s[6:7]
	v_rsq_f32_e32 v22, v22
	v_add_f32_e32 v23, 1.0, v41
	v_mul_f32_e32 v37, 0x45800000, v22
	v_cndmask_b32_e64 v56, v22, v37, s[6:7]
	v_mul_f32_e32 v7, v56, v7
	v_mul_f32_e32 v11, v56, v11
	v_mul_f32_e32 v22, v56, v68
	v_mul_f32_e32 v38, v56, v70
	v_mul_f32_e32 v37, v56, v69
	v_mul_f32_e32 v39, v56, v71
	v_mul_f32_e32 v40, v56, v72
	v_mul_f32_e32 v41, v56, v73
	s_waitcnt vmcnt(0)
	v_fma_f32 v7, v24, v7, v52
	v_fma_f32 v11, v25, v11, v53
	v_fma_f32 v24, v28, v22, v54
	v_fma_f32 v25, v30, v38, v48
	v_fmac_f32_e32 v55, v29, v37
	v_fma_f32 v28, v23, v39, v49
	v_fma_f32 v29, v31, v40, v50
	v_fmac_f32_e32 v51, v36, v41
	v_cvt_pk_bf16_f32 v22, v7, v11
	v_cvt_pk_bf16_f32 v23, v24, v55
	v_cvt_pk_bf16_f32 v24, v25, v28
	v_cvt_pk_bf16_f32 v25, v29, v51
	global_store_dwordx4 v[66:67], v[22:25], off
	v_and_b32_e32 v28, 0xffff0000, v32
	v_and_b32_e32 v30, 0xffff0000, v33
	v_lshlrev_b32_e32 v29, 16, v33
	v_and_b32_e32 v32, 0xffff0000, v34
	v_mul_f32_e32 v7, v28, v28
	v_mul_f32_e32 v11, v30, v30
	v_lshlrev_b32_e32 v31, 16, v34
	v_lshlrev_b32_e32 v33, 16, v35
	v_and_b32_e32 v34, 0xffff0000, v35
	v_mul_f32_e32 v35, v32, v32
	v_fmac_f32_e32 v7, v21, v21
	v_fmac_f32_e32 v11, v29, v29
	v_lshlrev_b32_e32 v27, 16, v44
	v_and_b32_e32 v26, 0xffff0000, v44
	v_mul_f32_e32 v44, v34, v34
	v_fmac_f32_e32 v35, v31, v31
	v_add_f32_e32 v7, v7, v11
	v_lshlrev_b32_e32 v25, 16, v45
	v_and_b32_e32 v24, 0xffff0000, v45
	v_mul_f32_e32 v45, v26, v26
	v_fmac_f32_e32 v44, v33, v33
	v_add_f32_e32 v7, v35, v7
	v_lshlrev_b32_e32 v23, 16, v46
	v_and_b32_e32 v22, 0xffff0000, v46
	v_mul_f32_e32 v46, v24, v24
	v_fmac_f32_e32 v45, v27, v27
	v_add_f32_e32 v7, v44, v7
	v_lshlrev_b32_e32 v13, 16, v47
	v_and_b32_e32 v12, 0xffff0000, v47
	v_mul_f32_e32 v47, v22, v22
	v_fmac_f32_e32 v46, v25, v25
	v_add_f32_e32 v7, v45, v7
	v_mul_f32_e32 v57, v12, v12
	v_fmac_f32_e32 v47, v23, v23
	v_add_f32_e32 v7, v46, v7
	v_fmac_f32_e32 v57, v13, v13
	v_add_f32_e32 v7, v47, v7
	v_add_f32_e32 v7, v57, v7
	ds_bpermute_b32 v11, v14, v7
	v_mul_f32_e32 v35, v56, v58
	v_mul_f32_e32 v44, v56, v60
	v_mul_f32_e32 v45, v56, v59
	v_mul_f32_e32 v46, v56, v61
	s_waitcnt lgkmcnt(0)
; __device__ __forceinline__ float bflo(unsigned w) { return __uint_as_float(w << 16); }
; __device__ __forceinline__ void norm_rows_b(const bf16_t* hb, int r_begin, int nrows, int stride, int second_off, const float* modl, int shoff, int scoff, bf16_t* xl) {
;     ...
;     for (int r = r_begin; r < nrows; r += stride) {
;         const int r1 = r + second_off; const bool two = r1 < nrows;
;         u32x4 w[2][2]; float s[2];
; #pragma unroll
;         for (int q = 0; q < 2; ++q) { const bf16_t* xr = hb + (size_t)(q ? (two ? r1 : r) : r) * DM + 8 * lane; w[q][0] = *(const u32x4*)(xr); w[q][1] = *(const u32x4*)(xr + 512); }
;         float v[2][16];
; #pragma unroll
;         for (int q = 0; q < 2; ++q) { float a = 0.f;
; #pragma unroll
;             for (int h = 0; h < 2; ++h)
; #pragma unroll
;                 for (int e = 0; e < 4; ++e) { const float lo = bflo(w[q][h][e]), hi = bfhi(w[q][h][e]); v[q][8 * h + 2 * e] = lo; v[q][8 * h + 2 * e + 1] = hi; a += lo * lo + hi * hi; }
;             s[q] = a; }
; #pragma unroll
;         for (int o = 32; o > 0; o >>= 1) { s[0] += __shfl_xor(s[0], o); s[1] += __shfl_xor(s[1], o); }
; #pragma unroll
;         for (int q = 0; q < 2; ++q) { if (q == 1 && !two) break; const int rr = q ? r1 : r; const int cond = rr < MLAT ? (rr >> 13) : 8; const float* mp = modl + cond * 6144;
;             const float rstd = rsqrtf(s[q] * (1.0f / DM) + EPS);
; #pragma unroll
;             for (int h = 0; h < 2; ++h) { const int col = 8 * lane + 512 * h; const f32x4 sc0 = *(const f32x4*)(mp + scoff + col), sc1 = *(const f32x4*)(mp + scoff + col + 4), sh0 = *(const f32x4*)(mp + shoff + col), sh1 = *(const f32x4*)(mp + shoff + col + 4);
;                 u32x4 o;
;                 o.x = cvt_pk_bf16(v[q][8 * h + 0] * rstd * (sc0[0] + 1.0f) + sh0[0], v[q][8 * h + 1] * rstd * (sc0[1] + 1.0f) + sh0[1]);
;                 o.y = cvt_pk_bf16(v[q][8 * h + 2] * rstd * (sc0[2] + 1.0f) + sh0[2], v[q][8 * h + 3] * rstd * (sc0[3] + 1.0f) + sh0[3]);
;                 o.z = cvt_pk_bf16(v[q][8 * h + 4] * rstd * (sc1[0] + 1.0f) + sh1[0], v[q][8 * h + 5] * rstd * (sc1[1] + 1.0f) + sh1[1]);
;                 o.w = cvt_pk_bf16(v[q][8 * h + 6] * rstd * (sc1[2] + 1.0f) + sh1[2], v[q][8 * h + 7] * rstd * (sc1[3] + 1.0f) + sh1[3]);
;                 *(u32x4*)(xl + (size_t)rr * DM + col) = o; } }
	v_add_f32_e32 v7, v7, v11
	ds_bpermute_b32 v11, v15, v7
	v_mul_f32_e32 v47, v56, v62
	v_mul_f32_e32 v57, v56, v64
	v_mul_f32_e32 v58, v56, v63
	v_mul_f32_e32 v56, v56, v65
	s_waitcnt lgkmcnt(0)
	v_add_f32_e32 v7, v7, v11
	ds_bpermute_b32 v11, v16, v7
	s_waitcnt lgkmcnt(0)
	v_add_f32_e32 v7, v7, v11
	ds_bpermute_b32 v11, v17, v7
	s_waitcnt lgkmcnt(0)
	v_add_f32_e32 v7, v7, v11
	ds_bpermute_b32 v11, v18, v7
	s_waitcnt lgkmcnt(0)
	v_add_f32_e32 v7, v7, v11
	ds_bpermute_b32 v11, v19, v7
	s_waitcnt vmcnt(9)
	v_add_f32_e32 v36, 1.0, v80
	s_waitcnt vmcnt(8)
	v_add_f32_e32 v40, 1.0, v84
	v_add_f32_e32 v41, 1.0, v85
	v_add_f32_e32 v42, 1.0, v86
	v_add_f32_e32 v43, 1.0, v87
	v_add_f32_e32 v37, 1.0, v81
	v_add_f32_e32 v38, 1.0, v82
	v_add_f32_e32 v39, 1.0, v83
	s_waitcnt vmcnt(3)
	v_fma_f32 v35, v40, v35, v92
	v_fma_f32 v40, v41, v44, v93
	v_fma_f32 v41, v42, v45, v94
	v_fma_f32 v55, v43, v46, v95
	v_fma_f32 v42, v47, v36, v88
	v_fma_f32 v43, v57, v37, v89
	v_fma_f32 v44, v58, v38, v90
	v_fma_f32 v51, v56, v39, v91
	v_cvt_pk_bf16_f32 v36, v35, v40
	v_cvt_pk_bf16_f32 v37, v41, v55
	v_cvt_pk_bf16_f32 v38, v42, v43
	v_cvt_pk_bf16_f32 v39, v44, v51
	global_store_dwordx4 v[66:67], v[36:39], off offset:1024
	s_and_saveexec_b64 s[6:7], vcc
	s_cbranch_execz .LBB0_334
	v_min_i32_e32 v35, 0x10000, v10
	v_ashrrev_i32_e32 v35, 13, v35
	v_mul_i32_i24_e32 v36, 0x1800, v35
	v_ashrrev_i32_e32 v37, 31, v36
	v_lshl_add_u64 v[44:45], v[36:37], 2, s[54:55]
	v_lshl_add_u64 v[52:53], v[44:45], 0, s[8:9]
	v_lshl_add_u64 v[40:41], v[52:53], 0, v[0:1]
	v_lshl_add_u64 v[54:55], v[44:45], 0, s[10:11]
	global_load_dwordx4 v[80:83], v[40:41], off offset:2048
	global_load_dwordx4 v[84:87], v[40:41], off offset:2064
	global_load_dwordx4 v[36:39], v[40:41], off
	s_nop 0
	global_load_dwordx4 v[40:43], v[40:41], off offset:16
	v_lshl_add_u64 v[48:49], v[54:55], 0, v[0:1]
	global_load_dwordx4 v[88:91], v[48:49], off offset:2048
	global_load_dwordx4 v[92:95], v[48:49], off offset:2064
	global_load_dwordx4 v[44:47], v[48:49], off
	s_nop 0
	global_load_dwordx4 v[48:51], v[48:49], off offset:16
	s_waitcnt lgkmcnt(0)
	v_add_f32_e32 v35, v7, v11
	v_fmamk_f32 v35, v35, 0x3a800000, v20
	v_mul_f32_e32 v56, 0x4b800000, v35
	v_cmp_gt_f32_e32 vcc, s13, v35
	v_ashrrev_i32_e32 v11, 31, v10
	v_mov_b32_e32 v7, v1
	v_cndmask_b32_e32 v35, v35, v56, vcc
	v_rsq_f32_e32 v35, v35
	v_lshlrev_b64 v[56:57], 11, v[10:11]
	v_lshl_add_u64 v[56:57], v[4:5], 0, v[56:57]
	v_lshl_add_u64 v[52:53], v[52:53], 0, v[6:7]
	v_mul_f32_e32 v11, 0x45800000, v35
	v_cndmask_b32_e32 v11, v35, v11, vcc
	v_mul_f32_e32 v28, v11, v28
	v_mul_f32_e32 v29, v11, v29
	v_mul_f32_e32 v30, v11, v30
	v_mul_f32_e32 v31, v11, v31
	v_mul_f32_e32 v32, v11, v32
	v_mul_f32_e32 v21, v11, v21
	v_mul_f32_e32 v33, v11, v33
	v_mul_f32_e32 v34, v11, v34
	v_mul_f32_e32 v25, v11, v25
	v_mul_f32_e32 v24, v11, v24
	v_mul_f32_e32 v23, v11, v23
	v_mul_f32_e32 v22, v11, v22
	v_mul_f32_e32 v13, v11, v13
	s_waitcnt vmcnt(5)
	v_add_f32_e32 v35, 1.0, v36
	v_add_f32_e32 v36, 1.0, v37
	v_add_f32_e32 v37, 1.0, v38
	v_add_f32_e32 v38, 1.0, v39
	s_waitcnt vmcnt(4)
	v_add_f32_e32 v39, 1.0, v40
	v_add_f32_e32 v40, 1.0, v41
	v_add_f32_e32 v41, 1.0, v42
	v_add_f32_e32 v42, 1.0, v43
	s_waitcnt vmcnt(1)
	v_fma_f32 v28, v28, v36, v45
	v_fma_f32 v29, v29, v37, v46
	v_fmac_f32_e32 v47, v30, v38
	s_waitcnt vmcnt(0)
	v_fma_f32 v30, v31, v39, v48
	v_fma_f32 v31, v32, v40, v49
	v_fma_f32 v21, v21, v35, v44
	v_fma_f32 v32, v33, v41, v50
	v_fmac_f32_e32 v51, v34, v42
	v_cvt_pk_bf16_f32 v28, v21, v28
	v_cvt_pk_bf16_f32 v29, v29, v47
	v_cvt_pk_bf16_f32 v30, v30, v31
	v_cvt_pk_bf16_f32 v31, v32, v51
	global_store_dwordx4 v[56:57], v[28:31], off
	s_nop 0
	v_lshl_add_u64 v[40:41], v[54:55], 0, v[6:7]
	s_nop 0
	v_mul_f32_e32 v7, v11, v27
	v_mul_f32_e32 v21, v11, v26
	v_mul_f32_e32 v11, v11, v12
	s_waitcnt vmcnt(8)
	v_add_f32_e32 v12, 1.0, v80
	v_add_f32_e32 v26, 1.0, v81
	v_add_f32_e32 v27, 1.0, v82
	v_add_f32_e32 v28, 1.0, v83
	s_waitcnt vmcnt(7)
	v_add_f32_e32 v29, 1.0, v84
	v_add_f32_e32 v30, 1.0, v85
	v_add_f32_e32 v31, 1.0, v86
	v_add_f32_e32 v32, 1.0, v87
	s_waitcnt vmcnt(4)
	v_fma_f32 v7, v7, v12, v88
	v_fma_f32 v12, v21, v26, v89
	v_fma_f32 v21, v25, v27, v90
	v_fma_f32 v39, v24, v28, v91
	s_waitcnt vmcnt(3)
	v_fma_f32 v24, v23, v29, v92
	v_fma_f32 v25, v22, v30, v93
	v_fma_f32 v13, v13, v31, v94
	v_fma_f32 v43, v11, v32, v95
	v_cvt_pk_bf16_f32 v22, v7, v12
	v_cvt_pk_bf16_f32 v23, v21, v39
	v_cvt_pk_bf16_f32 v24, v24, v25
	v_cvt_pk_bf16_f32 v25, v13, v43
	global_store_dwordx4 v[56:57], v[22:25], off offset:1024
	s_branch .LBB0_334

; __device__ __forceinline__ float bflo(unsigned w) { return __uint_as_float(w << 16); }
; __device__ __forceinline__ void norm_rows_b(const bf16_t* hb, int r_begin, int nrows, int stride, int second_off, const float* modl, int shoff, int scoff, bf16_t* xl) {
;     ...
;     for (int r = r_begin; r < nrows; r += stride) {
;         const int r1 = r + second_off; const bool two = r1 < nrows;
;         u32x4 w[2][2]; float s[2];
; #pragma unroll
;         for (int q = 0; q < 2; ++q) { const bf16_t* xr = hb + (size_t)(q ? (two ? r1 : r) : r) * DM + 8 * lane; w[q][0] = *(const u32x4*)(xr); w[q][1] = *(const u32x4*)(xr + 512); }
;         float v[2][16];
; #pragma unroll
;         for (int q = 0; q < 2; ++q) { float a = 0.f;
; #pragma unroll
;             for (int h = 0; h < 2; ++h)
; #pragma unroll
;                 for (int e = 0; e < 4; ++e) { const float lo = bflo(w[q][h][e]), hi = bfhi(w[q][h][e]); v[q][8 * h + 2 * e] = lo; v[q][8 * h + 2 * e + 1] = hi; a += lo * lo + hi * hi; }
;             s[q] = a; }
; #pragma unroll
;         for (int o = 32; o > 0; o >>= 1) { s[0] += __shfl_xor(s[0], o); s[1] += __shfl_xor(s[1], o); }
; #pragma unroll
;         for (int q = 0; q < 2; ++q) { if (q == 1 && !two) break; const int rr = q ? r1 : r; const int cond = rr < MLAT ? (rr >> 13) : 8; const float* mp = modl + cond * 6144;
;             const float rstd = rsqrtf(s[q] * (1.0f / DM) + EPS);
; #pragma unroll
;             for (int h = 0; h < 2; ++h) { const int col = 8 * lane + 512 * h; const f32x4 sc0 = *(const f32x4*)(mp + scoff + col), sc1 = *(const f32x4*)(mp + scoff + col + 4), sh0 = *(const f32x4*)(mp + shoff + col), sh1 = *(const f32x4*)(mp + shoff + col + 4);
;                 u32x4 o;
;                 o.x = cvt_pk_bf16(v[q][8 * h + 0] * rstd * (sc0[0] + 1.0f) + sh0[0], v[q][8 * h + 1] * rstd * (sc0[1] + 1.0f) + sh0[1]);
;                 o.y = cvt_pk_bf16(v[q][8 * h + 2] * rstd * (sc0[2] + 1.0f) + sh0[2], v[q][8 * h + 3] * rstd * (sc0[3] + 1.0f) + sh0[3]);
;                 o.z = cvt_pk_bf16(v[q][8 * h + 4] * rstd * (sc1[0] + 1.0f) + sh1[0], v[q][8 * h + 5] * rstd * (sc1[1] + 1.0f) + sh1[1]);
;                 o.w = cvt_pk_bf16(v[q][8 * h + 6] * rstd * (sc1[2] + 1.0f) + sh1[2], v[q][8 * h + 7] * rstd * (sc1[3] + 1.0f) + sh1[3]);
;                 *(u32x4*)(xl + (size_t)rr * DM + col) = o; } }
.LBB0_586:
	v_ashrrev_i32_e32 v13, 31, v12
	v_lshlrev_b64 v[56:57], 11, v[12:13]
	s_waitcnt lgkmcnt(0)
	v_lshl_add_u64 v[10:11], v[2:3], 0, v[56:57]
	global_load_dwordx4 v[14:17], v[10:11], off
	global_load_dwordx4 v[28:31], v[10:11], off offset:1024
	v_min_i32_e32 v7, 0x10000, v12
	v_add_u32_e32 v10, s28, v12
	v_ashrrev_i32_e32 v7, 13, v7
	v_cmp_gt_i32_e32 vcc, s20, v10
	v_mul_i32_i24_e32 v18, 0x1800, v7
	v_ashrrev_i32_e32 v19, 31, v18
	v_cndmask_b32_e32 v12, v12, v10, vcc
	v_ashrrev_i32_e32 v13, 31, v12
	v_lshl_add_u64 v[18:19], v[18:19], 2, s[16:17]
	v_lshlrev_b64 v[12:13], 11, v[12:13]
	v_lshl_add_u64 v[58:59], v[18:19], 0, s[14:15]
	v_lshl_add_u64 v[12:13], v[2:3], 0, v[12:13]
	v_lshl_add_u64 v[40:41], v[58:59], 0, v[0:1]
	global_load_dwordx4 v[32:35], v[12:13], off
	global_load_dwordx4 v[80:83], v[40:41], off offset:2064
	global_load_dwordx4 v[84:87], v[40:41], off offset:2048
	global_load_dwordx4 v[36:39], v[40:41], off
	s_nop 0
	global_load_dwordx4 v[40:43], v[40:41], off offset:16
	s_nop 0
	global_load_dwordx4 v[44:47], v[12:13], off offset:1024
	v_lshl_add_u64 v[60:61], v[18:19], 0, v[0:1]
	global_load_dwordx4 v[88:91], v[60:61], off offset:2064
	global_load_dwordx4 v[92:95], v[60:61], off offset:2048
	global_load_dwordx4 v[48:51], v[60:61], off offset:16
	global_load_dwordx4 v[52:55], v[60:61], off
	s_waitcnt vmcnt(11)
	v_and_b32_e32 v11, 0xffff0000, v14
	v_and_b32_e32 v63, 0xffff0000, v15
	v_lshlrev_b32_e32 v7, 16, v14
	v_lshlrev_b32_e32 v62, 16, v15
	v_and_b32_e32 v67, 0xffff0000, v16
	v_mul_f32_e32 v27, v11, v11
	v_mul_f32_e32 v64, v63, v63
	v_lshlrev_b32_e32 v66, 16, v16
	v_and_b32_e32 v69, 0xffff0000, v17
	v_mul_f32_e32 v65, v67, v67
	v_fmac_f32_e32 v27, v7, v7
	v_fmac_f32_e32 v64, v62, v62
	v_lshlrev_b32_e32 v68, 16, v17
	s_waitcnt vmcnt(10)
	v_and_b32_e32 v17, 0xffff0000, v29
	v_and_b32_e32 v16, 0xffff0000, v28
	v_mul_f32_e32 v70, v69, v69
	v_fmac_f32_e32 v65, v66, v66
	v_add_f32_e32 v27, v27, v64
	v_lshlrev_b32_e32 v19, 16, v29
	v_lshlrev_b32_e32 v18, 16, v28
	v_pk_mul_f32 v[28:29], v[16:17], v[16:17]
	v_fmac_f32_e32 v70, v68, v68
	v_add_f32_e32 v27, v65, v27
	v_and_b32_e32 v13, 0xffff0000, v31
	v_and_b32_e32 v12, 0xffff0000, v30
	v_pk_fma_f32 v[28:29], v[18:19], v[18:19], v[28:29]
	v_add_f32_e32 v27, v70, v27
	v_lshlrev_b32_e32 v15, 16, v31
	v_lshlrev_b32_e32 v14, 16, v30
	v_pk_mul_f32 v[30:31], v[12:13], v[12:13]
	v_add_f32_e32 v27, v28, v27
	v_pk_fma_f32 v[30:31], v[14:15], v[14:15], v[30:31]
	v_add_f32_e32 v27, v29, v27
	v_add_f32_e32 v27, v30, v27
	v_add_f32_e32 v27, v31, v27
	ds_bpermute_b32 v28, v20, v27
	s_waitcnt vmcnt(6)
	v_add_f32_e32 v30, 1.0, v36
	v_add_f32_e32 v36, 1.0, v38
	s_waitcnt vmcnt(5)
	v_add_f32_e32 v38, 1.0, v40
	v_add_f32_e32 v40, 1.0, v43
	s_waitcnt lgkmcnt(0)
	v_add_f32_e32 v27, v27, v28
	ds_bpermute_b32 v28, v21, v27
	v_add_f32_e32 v31, 1.0, v37
	v_add_f32_e32 v37, 1.0, v39
	v_add_f32_e32 v39, 1.0, v42
	v_lshl_add_u64 v[64:65], v[4:5], 0, v[56:57]
	s_waitcnt lgkmcnt(0)
	v_add_f32_e32 v27, v27, v28
	ds_bpermute_b32 v28, v22, v27
	v_lshl_add_u64 v[56:57], v[58:59], 0, v[8:9]
	s_waitcnt lgkmcnt(0)
	v_add_f32_e32 v27, v27, v28
	ds_bpermute_b32 v28, v23, v27
	s_waitcnt lgkmcnt(0)
	v_add_f32_e32 v28, v27, v28
	ds_bpermute_b32 v29, v24, v28
	v_lshlrev_b32_e32 v27, 16, v32
	s_waitcnt lgkmcnt(0)
	v_add_f32_e32 v28, v28, v29
	ds_bpermute_b32 v29, v25, v28
	s_waitcnt lgkmcnt(0)
	v_add_f32_e32 v28, v28, v29
	v_fmamk_f32 v28, v28, 0x3a800000, v26
	v_mul_f32_e32 v29, 0x4b800000, v28
	v_cmp_gt_f32_e64 s[38:39], s21, v28
	s_nop 1
	v_cndmask_b32_e64 v28, v28, v29, s[38:39]
	v_rsq_f32_e32 v28, v28
	v_add_f32_e32 v29, 1.0, v41
	v_mul_f32_e32 v41, 0x45800000, v28
	v_cndmask_b32_e64 v43, v28, v41, s[38:39]
	v_mul_f32_e32 v7, v43, v7
	v_mul_f32_e32 v11, v43, v11
	v_mul_f32_e32 v28, v43, v62
	v_mul_f32_e32 v42, v43, v66
	v_mul_f32_e32 v41, v43, v63
	v_mul_f32_e32 v58, v43, v67
	v_mul_f32_e32 v59, v43, v68
	v_mul_f32_e32 v62, v43, v69
	s_waitcnt vmcnt(0)
	v_fma_f32 v7, v30, v7, v52
	v_fma_f32 v11, v31, v11, v53
	v_fma_f32 v30, v36, v28, v54
	v_fma_f32 v31, v38, v42, v48
	v_fmac_f32_e32 v55, v37, v41
	v_fma_f32 v36, v29, v58, v49
	v_fma_f32 v37, v39, v59, v50
	v_fmac_f32_e32 v51, v40, v62
	v_cvt_pk_bf16_f32 v28, v7, v11
	v_cvt_pk_bf16_f32 v29, v30, v55
	v_cvt_pk_bf16_f32 v30, v31, v36
	v_cvt_pk_bf16_f32 v31, v37, v51
	global_store_dwordx4 v[64:65], v[28:31], off
	s_nop 0
	s_nop 0
	v_and_b32_e32 v28, 0xffff0000, v32
	v_and_b32_e32 v38, 0xffff0000, v33
	v_lshlrev_b32_e32 v37, 16, v33
	v_and_b32_e32 v40, 0xffff0000, v34
	v_mul_f32_e32 v7, v28, v28
	v_mul_f32_e32 v11, v38, v38
	v_lshlrev_b32_e32 v39, 16, v34
	v_lshlrev_b32_e32 v41, 16, v35
	v_and_b32_e32 v42, 0xffff0000, v35
	v_lshlrev_b32_e32 v36, 16, v44
	v_and_b32_e32 v35, 0xffff0000, v44
	v_mul_f32_e32 v44, v40, v40
	v_fmac_f32_e32 v7, v27, v27
	v_fmac_f32_e32 v11, v37, v37
	v_lshlrev_b32_e32 v34, 16, v45
	v_and_b32_e32 v33, 0xffff0000, v45
	v_mul_f32_e32 v45, v42, v42
	v_fmac_f32_e32 v44, v39, v39
	v_add_f32_e32 v7, v7, v11
	v_lshlrev_b32_e32 v32, 16, v46
	v_and_b32_e32 v31, 0xffff0000, v46
	v_mul_f32_e32 v46, v35, v35
	v_fmac_f32_e32 v45, v41, v41
	v_add_f32_e32 v7, v44, v7
	v_lshlrev_b32_e32 v30, 16, v47
	v_and_b32_e32 v29, 0xffff0000, v47
	v_mul_f32_e32 v47, v33, v33
	v_fmac_f32_e32 v46, v36, v36
	v_add_f32_e32 v7, v45, v7
	v_mul_f32_e32 v66, v31, v31
	v_fmac_f32_e32 v47, v34, v34
	v_add_f32_e32 v7, v46, v7
	v_mul_f32_e32 v67, v29, v29
	v_fmac_f32_e32 v66, v32, v32
	v_add_f32_e32 v7, v47, v7
	v_fmac_f32_e32 v67, v30, v30
	v_add_f32_e32 v7, v66, v7
	v_add_f32_e32 v7, v67, v7
	ds_bpermute_b32 v11, v20, v7
	v_mul_f32_e32 v14, v43, v14
	v_mul_f32_e32 v15, v43, v15
	v_mul_f32_e32 v18, v43, v18
	v_mul_f32_e32 v16, v43, v16
	s_waitcnt lgkmcnt(0)
	v_add_f32_e32 v7, v7, v11
	ds_bpermute_b32 v11, v21, v7
	v_mul_f32_e32 v19, v43, v19
	v_mul_f32_e32 v17, v43, v17
	v_mul_f32_e32 v12, v43, v12
	v_mul_f32_e32 v13, v43, v13
	s_waitcnt lgkmcnt(0)
	v_add_f32_e32 v7, v7, v11
	ds_bpermute_b32 v11, v22, v7
	s_waitcnt lgkmcnt(0)
	v_add_f32_e32 v7, v7, v11
	ds_bpermute_b32 v11, v23, v7
	s_waitcnt lgkmcnt(0)
	v_add_f32_e32 v7, v7, v11
	ds_bpermute_b32 v11, v24, v7
	s_waitcnt lgkmcnt(0)
	v_add_f32_e32 v7, v7, v11
	ds_bpermute_b32 v11, v25, v7
	s_waitcnt vmcnt(9)
	v_add_f32_e32 v47, 1.0, v80
	v_add_f32_e32 v48, 1.0, v81
	v_add_f32_e32 v49, 1.0, v82
	s_waitcnt vmcnt(8)
	v_add_f32_e32 v43, 1.0, v84
	v_add_f32_e32 v44, 1.0, v85
	v_add_f32_e32 v45, 1.0, v86
	v_add_f32_e32 v46, 1.0, v87
	v_add_f32_e32 v50, 1.0, v83
	s_waitcnt vmcnt(4)
	v_fma_f32 v14, v14, v47, v88
	v_fma_f32 v15, v15, v49, v90
	s_waitcnt vmcnt(3)
	v_fma_f32 v18, v43, v18, v92
	v_fma_f32 v16, v44, v16, v93
	v_fma_f32 v19, v45, v19, v94
	v_fma_f32 v63, v46, v17, v95
	v_fma_f32 v17, v12, v48, v89
	v_fma_f32 v59, v13, v50, v91
	v_cvt_pk_bf16_f32 v12, v18, v16
	v_cvt_pk_bf16_f32 v13, v19, v63
	v_cvt_pk_bf16_f32 v14, v14, v17
	v_cvt_pk_bf16_f32 v15, v15, v59
	global_store_dwordx4 v[64:65], v[12:15], off offset:1024
	s_and_saveexec_b64 s[18:19], vcc
	s_cbranch_execz .LBB0_585
; __device__ __forceinline__ float bflo(unsigned w) { return __uint_as_float(w << 16); }
; __device__ __forceinline__ void norm_rows_b(const bf16_t* hb, int r_begin, int nrows, int stride, int second_off, const float* modl, int shoff, int scoff, bf16_t* xl) {
;     ...
;     for (int r = r_begin; r < nrows; r += stride) {
;         const int r1 = r + second_off; const bool two = r1 < nrows;
;         u32x4 w[2][2]; float s[2];
; #pragma unroll
;         for (int q = 0; q < 2; ++q) { const bf16_t* xr = hb + (size_t)(q ? (two ? r1 : r) : r) * DM + 8 * lane; w[q][0] = *(const u32x4*)(xr); w[q][1] = *(const u32x4*)(xr + 512); }
;         float v[2][16];
; #pragma unroll
;         for (int q = 0; q < 2; ++q) { float a = 0.f;
; #pragma unroll
;             for (int h = 0; h < 2; ++h)
; #pragma unroll
;                 for (int e = 0; e < 4; ++e) { const float lo = bflo(w[q][h][e]), hi = bfhi(w[q][h][e]); v[q][8 * h + 2 * e] = lo; v[q][8 * h + 2 * e + 1] = hi; a += lo * lo + hi * hi; }
;             s[q] = a; }
; #pragma unroll
;         for (int o = 32; o > 0; o >>= 1) { s[0] += __shfl_xor(s[0], o); s[1] += __shfl_xor(s[1], o); }
; #pragma unroll
;         for (int q = 0; q < 2; ++q) { if (q == 1 && !two) break; const int rr = q ? r1 : r; const int cond = rr < MLAT ? (rr >> 13) : 8; const float* mp = modl + cond * 6144;
;             const float rstd = rsqrtf(s[q] * (1.0f / DM) + EPS);
; #pragma unroll
;             for (int h = 0; h < 2; ++h) { const int col = 8 * lane + 512 * h; const f32x4 sc0 = *(const f32x4*)(mp + scoff + col), sc1 = *(const f32x4*)(mp + scoff + col + 4), sh0 = *(const f32x4*)(mp + shoff + col), sh1 = *(const f32x4*)(mp + shoff + col + 4);
;                 u32x4 o;
;                 o.x = cvt_pk_bf16(v[q][8 * h + 0] * rstd * (sc0[0] + 1.0f) + sh0[0], v[q][8 * h + 1] * rstd * (sc0[1] + 1.0f) + sh0[1]);
;                 o.y = cvt_pk_bf16(v[q][8 * h + 2] * rstd * (sc0[2] + 1.0f) + sh0[2], v[q][8 * h + 3] * rstd * (sc0[3] + 1.0f) + sh0[3]);
;                 o.z = cvt_pk_bf16(v[q][8 * h + 4] * rstd * (sc1[0] + 1.0f) + sh1[0], v[q][8 * h + 5] * rstd * (sc1[1] + 1.0f) + sh1[1]);
;                 o.w = cvt_pk_bf16(v[q][8 * h + 6] * rstd * (sc1[2] + 1.0f) + sh1[2], v[q][8 * h + 7] * rstd * (sc1[3] + 1.0f) + sh1[3]);
;                 *(u32x4*)(xl + (size_t)rr * DM + col) = o; } }
	v_min_i32_e32 v12, 0x10000, v10
	v_ashrrev_i32_e32 v12, 13, v12
	v_mul_i32_i24_e32 v12, 0x1800, v12
	v_ashrrev_i32_e32 v13, 31, v12
	v_lshl_add_u64 v[44:45], v[12:13], 2, s[16:17]
	v_lshl_add_u64 v[52:53], v[44:45], 0, s[14:15]
	v_lshl_add_u64 v[16:17], v[52:53], 0, v[0:1]
	global_load_dwordx4 v[80:83], v[16:17], off offset:2048
	global_load_dwordx4 v[84:87], v[16:17], off offset:2064
	global_load_dwordx4 v[12:15], v[16:17], off
	s_nop 0
	global_load_dwordx4 v[16:19], v[16:17], off offset:16
	v_lshl_add_u64 v[54:55], v[44:45], 0, v[0:1]
	global_load_dwordx4 v[88:91], v[54:55], off offset:2048
	global_load_dwordx4 v[92:95], v[54:55], off offset:2064
	global_load_dwordx4 v[44:47], v[54:55], off
	global_load_dwordx4 v[48:51], v[54:55], off offset:16
	s_waitcnt lgkmcnt(0)
	v_add_f32_e32 v43, v7, v11
	v_fmamk_f32 v43, v43, 0x3a800000, v26
	v_mul_f32_e32 v56, 0x4b800000, v43
	v_cmp_gt_f32_e32 vcc, s21, v43
	v_mov_b32_e32 v7, v1
	v_lshl_add_u64 v[52:53], v[52:53], 0, v[6:7]
	v_cndmask_b32_e32 v43, v43, v56, vcc
	v_rsq_f32_e32 v43, v43
	v_ashrrev_i32_e32 v11, 31, v10
	v_lshlrev_b64 v[56:57], 11, v[10:11]
	v_lshl_add_u64 v[56:57], v[4:5], 0, v[56:57]
	v_mul_f32_e32 v7, 0x45800000, v43
	v_cndmask_b32_e32 v7, v43, v7, vcc
	v_mul_f32_e32 v11, v7, v27
	v_mul_f32_e32 v27, v7, v28
	v_mul_f32_e32 v28, v7, v37
	v_mul_f32_e32 v37, v7, v38
	v_mul_f32_e32 v38, v7, v39
	v_mul_f32_e32 v39, v7, v40
	v_mul_f32_e32 v40, v7, v41
	v_mul_f32_e32 v41, v7, v42
	v_mul_f32_e32 v33, v7, v33
	v_mul_f32_e32 v32, v7, v32
	v_mul_f32_e32 v31, v7, v31
	v_mul_f32_e32 v30, v7, v30
	s_waitcnt vmcnt(5)
	v_add_f32_e32 v12, 1.0, v12
	v_add_f32_e32 v13, 1.0, v13
	v_add_f32_e32 v14, 1.0, v14
	v_add_f32_e32 v15, 1.0, v15
	s_waitcnt vmcnt(4)
	v_add_f32_e32 v16, 1.0, v16
	v_add_f32_e32 v17, 1.0, v17
	v_add_f32_e32 v18, 1.0, v18
	v_add_f32_e32 v19, 1.0, v19
	s_waitcnt vmcnt(1)
	v_fma_f32 v11, v11, v12, v44
	v_fma_f32 v12, v27, v13, v45
	v_fma_f32 v13, v28, v14, v46
	v_fmac_f32_e32 v47, v37, v15
	s_waitcnt vmcnt(0)
	v_fma_f32 v14, v38, v16, v48
	v_fma_f32 v15, v39, v17, v49
	v_fma_f32 v16, v40, v18, v50
	v_fmac_f32_e32 v51, v41, v19
	v_cvt_pk_bf16_f32 v12, v11, v12
	v_cvt_pk_bf16_f32 v13, v13, v47
	v_cvt_pk_bf16_f32 v14, v14, v15
	v_cvt_pk_bf16_f32 v15, v16, v51
	global_store_dwordx4 v[56:57], v[12:15], off
	s_nop 0
	v_mul_f32_e32 v11, v7, v36
	v_mul_f32_e32 v27, v7, v35
	v_mul_f32_e32 v28, v7, v34
	v_mul_f32_e32 v7, v7, v29
	s_waitcnt vmcnt(8)
	v_add_f32_e32 v12, 1.0, v80
	v_add_f32_e32 v13, 1.0, v81
	v_add_f32_e32 v14, 1.0, v82
	v_add_f32_e32 v15, 1.0, v83
	s_waitcnt vmcnt(7)
	v_add_f32_e32 v16, 1.0, v84
	v_add_f32_e32 v17, 1.0, v85
	v_add_f32_e32 v18, 1.0, v86
	v_add_f32_e32 v19, 1.0, v87
	s_waitcnt vmcnt(4)
	v_fma_f32 v11, v11, v12, v88
	v_fma_f32 v12, v27, v13, v89
	v_fma_f32 v13, v28, v14, v90
	v_fma_f32 v41, v33, v15, v91
	s_waitcnt vmcnt(3)
	v_fma_f32 v14, v32, v16, v92
	v_fma_f32 v15, v31, v17, v93
	v_fma_f32 v16, v30, v18, v94
	v_fma_f32 v45, v7, v19, v95
	v_cvt_pk_bf16_f32 v12, v11, v12
	v_cvt_pk_bf16_f32 v13, v13, v41
	v_cvt_pk_bf16_f32 v14, v14, v15
	v_cvt_pk_bf16_f32 v15, v16, v45
	global_store_dwordx4 v[56:57], v[12:15], off offset:1024
	s_branch .LBB0_585

; __device__ __forceinline__ float bflo(unsigned w) { return __uint_as_float(w << 16); }
; __device__ __forceinline__ void norm_rows_b(const bf16_t* hb, int r_begin, int nrows, int stride, int second_off, const float* modl, int shoff, int scoff, bf16_t* xl) {
;     ...
;     for (int r = r_begin; r < nrows; r += stride) {
;         const int r1 = r + second_off; const bool two = r1 < nrows;
;         u32x4 w[2][2]; float s[2];
; #pragma unroll
;         for (int q = 0; q < 2; ++q) { const bf16_t* xr = hb + (size_t)(q ? (two ? r1 : r) : r) * DM + 8 * lane; w[q][0] = *(const u32x4*)(xr); w[q][1] = *(const u32x4*)(xr + 512); }
;         float v[2][16];
; #pragma unroll
;         for (int q = 0; q < 2; ++q) { float a = 0.f;
; #pragma unroll
;             for (int h = 0; h < 2; ++h)
; #pragma unroll
;                 for (int e = 0; e < 4; ++e) { const float lo = bflo(w[q][h][e]), hi = bfhi(w[q][h][e]); v[q][8 * h + 2 * e] = lo; v[q][8 * h + 2 * e + 1] = hi; a += lo * lo + hi * hi; }
;             s[q] = a; }
; #pragma unroll
;         for (int o = 32; o > 0; o >>= 1) { s[0] += __shfl_xor(s[0], o); s[1] += __shfl_xor(s[1], o); }
; #pragma unroll
;         for (int q = 0; q < 2; ++q) { if (q == 1 && !two) break; const int rr = q ? r1 : r; const int cond = rr < MLAT ? (rr >> 13) : 8; const float* mp = modl + cond * 6144;
;             const float rstd = rsqrtf(s[q] * (1.0f / DM) + EPS);
; #pragma unroll
;             for (int h = 0; h < 2; ++h) { const int col = 8 * lane + 512 * h; const f32x4 sc0 = *(const f32x4*)(mp + scoff + col), sc1 = *(const f32x4*)(mp + scoff + col + 4), sh0 = *(const f32x4*)(mp + shoff + col), sh1 = *(const f32x4*)(mp + shoff + col + 4);
;                 u32x4 o;
;                 o.x = cvt_pk_bf16(v[q][8 * h + 0] * rstd * (sc0[0] + 1.0f) + sh0[0], v[q][8 * h + 1] * rstd * (sc0[1] + 1.0f) + sh0[1]);
;                 o.y = cvt_pk_bf16(v[q][8 * h + 2] * rstd * (sc0[2] + 1.0f) + sh0[2], v[q][8 * h + 3] * rstd * (sc0[3] + 1.0f) + sh0[3]);
;                 o.z = cvt_pk_bf16(v[q][8 * h + 4] * rstd * (sc1[0] + 1.0f) + sh1[0], v[q][8 * h + 5] * rstd * (sc1[1] + 1.0f) + sh1[1]);
;                 o.w = cvt_pk_bf16(v[q][8 * h + 6] * rstd * (sc1[2] + 1.0f) + sh1[2], v[q][8 * h + 7] * rstd * (sc1[3] + 1.0f) + sh1[3]);
;                 *(u32x4*)(xl + (size_t)rr * DM + col) = o; } }
.LBB0_984:
	v_ashrrev_i32_e32 v13, 31, v12
	v_lshlrev_b64 v[50:51], 11, v[12:13]
	s_waitcnt lgkmcnt(0)
	v_lshl_add_u64 v[10:11], v[2:3], 0, v[50:51]
	global_load_dwordx4 v[18:21], v[10:11], off
	global_load_dwordx4 v[22:25], v[10:11], off offset:1024
	v_add_u32_e32 v10, s34, v12
	v_ashrrev_i32_e32 v7, 13, v12
	v_cmp_gt_i32_e32 vcc, s22, v10
	v_mul_i32_i24_e32 v14, 0x1800, v7
	v_ashrrev_i32_e32 v15, 31, v14
	v_cndmask_b32_e32 v12, v12, v10, vcc
	v_ashrrev_i32_e32 v13, 31, v12
	v_lshl_add_u64 v[14:15], v[14:15], 2, s[16:17]
	v_lshlrev_b64 v[12:13], 11, v[12:13]
	v_lshl_add_u64 v[52:53], v[14:15], 0, s[18:19]
	v_lshl_add_u64 v[12:13], v[2:3], 0, v[12:13]
	v_lshl_add_u64 v[34:35], v[52:53], 0, v[0:1]
	global_load_dwordx4 v[30:33], v[12:13], off
	global_load_dwordx4 v[80:83], v[34:35], off offset:2064
	global_load_dwordx4 v[84:87], v[34:35], off offset:2048
	global_load_dwordx4 v[26:29], v[34:35], off
	s_nop 0
	global_load_dwordx4 v[34:37], v[34:35], off offset:16
	v_lshl_add_u64 v[54:55], v[14:15], 0, s[20:21]
	global_load_dwordx4 v[38:41], v[12:13], off offset:1024
	v_lshl_add_u64 v[12:13], v[54:55], 0, v[0:1]
	global_load_dwordx4 v[88:91], v[12:13], off offset:2064
	global_load_dwordx4 v[92:95], v[12:13], off offset:2048
	global_load_dwordx4 v[42:45], v[12:13], off offset:16
	global_load_dwordx4 v[46:49], v[12:13], off
	v_lshl_add_u64 v[60:61], v[4:5], 0, v[50:51]
	v_lshl_add_u64 v[50:51], v[54:55], 0, v[8:9]
	s_waitcnt vmcnt(11)
	v_and_b32_e32 v11, 0xffff0000, v18
	v_and_b32_e32 v63, 0xffff0000, v19
	v_lshlrev_b32_e32 v7, 16, v18
	v_lshlrev_b32_e32 v62, 16, v19
	v_and_b32_e32 v65, 0xffff0000, v20
	s_waitcnt vmcnt(10)
	v_lshlrev_b32_e32 v56, 16, v22
	v_and_b32_e32 v58, 0xffff0000, v22
	v_mul_f32_e32 v17, v11, v11
	v_mul_f32_e32 v22, v63, v63
	v_lshlrev_b32_e32 v64, 16, v20
	v_and_b32_e32 v67, 0xffff0000, v21
	v_lshlrev_b32_e32 v57, 16, v23
	v_and_b32_e32 v59, 0xffff0000, v23
	v_mul_f32_e32 v23, v65, v65
	v_fmac_f32_e32 v17, v7, v7
	v_fmac_f32_e32 v22, v62, v62
	v_lshlrev_b32_e32 v66, 16, v21
	v_lshlrev_b32_e32 v14, 16, v24
	v_and_b32_e32 v12, 0xffff0000, v24
	v_mul_f32_e32 v24, v67, v67
	v_fmac_f32_e32 v23, v64, v64
	v_add_f32_e32 v17, v17, v22
	v_pk_mul_f32 v[18:19], v[58:59], v[58:59]
	v_fmac_f32_e32 v24, v66, v66
	v_add_f32_e32 v17, v23, v17
	v_and_b32_e32 v13, 0xffff0000, v25
	v_pk_fma_f32 v[18:19], v[56:57], v[56:57], v[18:19]
	v_add_f32_e32 v17, v24, v17
	v_lshlrev_b32_e32 v15, 16, v25
	v_pk_mul_f32 v[20:21], v[12:13], v[12:13]
	v_add_f32_e32 v17, v18, v17
	v_pk_fma_f32 v[20:21], v[14:15], v[14:15], v[20:21]
	v_add_f32_e32 v17, v19, v17
	v_add_f32_e32 v17, v20, v17
	v_add_f32_e32 v17, v21, v17
	ds_bpermute_b32 v18, v205, v17
	s_waitcnt vmcnt(6)
	v_add_f32_e32 v25, 1.0, v29
	v_add_f32_e32 v20, 1.0, v26
	v_add_f32_e32 v21, 1.0, v27
	v_add_f32_e32 v24, 1.0, v28
	s_waitcnt lgkmcnt(0)
	v_add_f32_e32 v17, v17, v18
	ds_bpermute_b32 v18, v206, v17
	s_waitcnt vmcnt(5)
	v_add_f32_e32 v26, 1.0, v34
	v_add_f32_e32 v27, 1.0, v36
	v_add_f32_e32 v28, 1.0, v37
	v_lshl_add_u64 v[22:23], v[52:53], 0, v[8:9]
	s_waitcnt lgkmcnt(0)
	v_add_f32_e32 v17, v17, v18
	ds_bpermute_b32 v18, v207, v17
	s_waitcnt lgkmcnt(0)
	v_add_f32_e32 v17, v17, v18
	ds_bpermute_b32 v18, v208, v17
	s_waitcnt lgkmcnt(0)
	v_add_f32_e32 v18, v17, v18
	ds_bpermute_b32 v19, v209, v18
	v_lshlrev_b32_e32 v17, 16, v30
	s_waitcnt lgkmcnt(0)
	v_add_f32_e32 v18, v18, v19
	ds_bpermute_b32 v19, v210, v18
	s_waitcnt lgkmcnt(0)
	v_add_f32_e32 v18, v18, v19
	v_fmamk_f32 v18, v18, 0x3a800000, v16
	v_mul_f32_e32 v19, 0x4b800000, v18
	v_cmp_gt_f32_e64 s[2:3], s23, v18
	s_nop 1
	v_cndmask_b32_e64 v18, v18, v19, s[2:3]
	v_rsq_f32_e32 v18, v18
	v_add_f32_e32 v19, 1.0, v35
	v_mul_f32_e32 v29, 0x45800000, v18
	v_cndmask_b32_e64 v54, v18, v29, s[2:3]
	v_mul_f32_e32 v7, v54, v7
	v_mul_f32_e32 v11, v54, v11
	v_mul_f32_e32 v18, v54, v62
	v_mul_f32_e32 v34, v54, v64
	v_mul_f32_e32 v29, v54, v63
	v_mul_f32_e32 v35, v54, v65
	v_mul_f32_e32 v36, v54, v66
	v_mul_f32_e32 v37, v54, v67
	s_waitcnt vmcnt(0)
	v_fma_f32 v7, v20, v7, v46
	v_fma_f32 v11, v21, v11, v47
	v_fma_f32 v20, v24, v18, v48
	v_fma_f32 v21, v26, v34, v42
	v_fmac_f32_e32 v49, v25, v29
	v_fma_f32 v24, v19, v35, v43
	v_fma_f32 v25, v27, v36, v44
	v_fmac_f32_e32 v45, v28, v37
	v_cvt_pk_bf16_f32 v18, v7, v11
	v_cvt_pk_bf16_f32 v19, v20, v49
	v_cvt_pk_bf16_f32 v20, v21, v24
	v_cvt_pk_bf16_f32 v21, v25, v45
	global_store_dwordx4 v[60:61], v[18:21], off
	s_nop 0
	v_and_b32_e32 v24, 0xffff0000, v30
	v_and_b32_e32 v28, 0xffff0000, v31
	v_lshlrev_b32_e32 v27, 16, v31
	v_and_b32_e32 v30, 0xffff0000, v32
	v_mul_f32_e32 v7, v24, v24
	v_mul_f32_e32 v11, v28, v28
	v_lshlrev_b32_e32 v29, 16, v32
	v_lshlrev_b32_e32 v31, 16, v33
	v_and_b32_e32 v32, 0xffff0000, v33
	v_mul_f32_e32 v33, v30, v30
	v_fmac_f32_e32 v7, v17, v17
	v_fmac_f32_e32 v11, v27, v27
	v_lshlrev_b32_e32 v26, 16, v38
	v_and_b32_e32 v25, 0xffff0000, v38
	v_mul_f32_e32 v38, v32, v32
	v_fmac_f32_e32 v33, v29, v29
	v_add_f32_e32 v7, v7, v11
	v_lshlrev_b32_e32 v23, 16, v39
	v_and_b32_e32 v22, 0xffff0000, v39
	v_mul_f32_e32 v39, v25, v25
	v_fmac_f32_e32 v38, v31, v31
	v_add_f32_e32 v7, v33, v7
	v_lshlrev_b32_e32 v21, 16, v40
	v_and_b32_e32 v20, 0xffff0000, v40
	v_mul_f32_e32 v40, v22, v22
	v_fmac_f32_e32 v39, v26, v26
	v_add_f32_e32 v7, v38, v7
	v_lshlrev_b32_e32 v19, 16, v41
	v_and_b32_e32 v18, 0xffff0000, v41
	v_mul_f32_e32 v41, v20, v20
	v_fmac_f32_e32 v40, v23, v23
	v_add_f32_e32 v7, v39, v7
	v_mul_f32_e32 v55, v18, v18
	v_fmac_f32_e32 v41, v21, v21
	v_add_f32_e32 v7, v40, v7
	v_fmac_f32_e32 v55, v19, v19
	v_add_f32_e32 v7, v41, v7
	v_add_f32_e32 v7, v55, v7
	ds_bpermute_b32 v11, v205, v7
	v_mul_f32_e32 v14, v54, v14
	v_mul_f32_e32 v15, v54, v15
	v_mul_f32_e32 v33, v54, v56
	v_mul_f32_e32 v38, v54, v58
	s_waitcnt lgkmcnt(0)
; __device__ __forceinline__ float bflo(unsigned w) { return __uint_as_float(w << 16); }
; __device__ __forceinline__ void norm_rows_b(const bf16_t* hb, int r_begin, int nrows, int stride, int second_off, const float* modl, int shoff, int scoff, bf16_t* xl) {
;     ...
;     for (int r = r_begin; r < nrows; r += stride) {
;         const int r1 = r + second_off; const bool two = r1 < nrows;
;         u32x4 w[2][2]; float s[2];
; #pragma unroll
;         for (int q = 0; q < 2; ++q) { const bf16_t* xr = hb + (size_t)(q ? (two ? r1 : r) : r) * DM + 8 * lane; w[q][0] = *(const u32x4*)(xr); w[q][1] = *(const u32x4*)(xr + 512); }
;         float v[2][16];
; #pragma unroll
;         for (int q = 0; q < 2; ++q) { float a = 0.f;
; #pragma unroll
;             for (int h = 0; h < 2; ++h)
; #pragma unroll
;                 for (int e = 0; e < 4; ++e) { const float lo = bflo(w[q][h][e]), hi = bfhi(w[q][h][e]); v[q][8 * h + 2 * e] = lo; v[q][8 * h + 2 * e + 1] = hi; a += lo * lo + hi * hi; }
;             s[q] = a; }
; #pragma unroll
;         for (int o = 32; o > 0; o >>= 1) { s[0] += __shfl_xor(s[0], o); s[1] += __shfl_xor(s[1], o); }
; #pragma unroll
;         for (int q = 0; q < 2; ++q) { if (q == 1 && !two) break; const int rr = q ? r1 : r; const int cond = rr < MLAT ? (rr >> 13) : 8; const float* mp = modl + cond * 6144;
;             const float rstd = rsqrtf(s[q] * (1.0f / DM) + EPS);
; #pragma unroll
;             for (int h = 0; h < 2; ++h) { const int col = 8 * lane + 512 * h; const f32x4 sc0 = *(const f32x4*)(mp + scoff + col), sc1 = *(const f32x4*)(mp + scoff + col + 4), sh0 = *(const f32x4*)(mp + shoff + col), sh1 = *(const f32x4*)(mp + shoff + col + 4);
;                 u32x4 o;
;                 o.x = cvt_pk_bf16(v[q][8 * h + 0] * rstd * (sc0[0] + 1.0f) + sh0[0], v[q][8 * h + 1] * rstd * (sc0[1] + 1.0f) + sh0[1]);
;                 o.y = cvt_pk_bf16(v[q][8 * h + 2] * rstd * (sc0[2] + 1.0f) + sh0[2], v[q][8 * h + 3] * rstd * (sc0[3] + 1.0f) + sh0[3]);
;                 o.z = cvt_pk_bf16(v[q][8 * h + 4] * rstd * (sc1[0] + 1.0f) + sh1[0], v[q][8 * h + 5] * rstd * (sc1[1] + 1.0f) + sh1[1]);
;                 o.w = cvt_pk_bf16(v[q][8 * h + 6] * rstd * (sc1[2] + 1.0f) + sh1[2], v[q][8 * h + 7] * rstd * (sc1[3] + 1.0f) + sh1[3]);
;                 *(u32x4*)(xl + (size_t)rr * DM + col) = o; } }
	v_add_f32_e32 v7, v7, v11
	ds_bpermute_b32 v11, v206, v7
	v_mul_f32_e32 v39, v54, v57
	v_mul_f32_e32 v40, v54, v59
	v_mul_f32_e32 v12, v54, v12
	v_mul_f32_e32 v13, v54, v13
	s_waitcnt lgkmcnt(0)
	v_add_f32_e32 v7, v7, v11
	ds_bpermute_b32 v11, v207, v7
	s_waitcnt lgkmcnt(0)
	v_add_f32_e32 v7, v7, v11
	ds_bpermute_b32 v11, v208, v7
	s_waitcnt lgkmcnt(0)
	v_add_f32_e32 v7, v7, v11
	ds_bpermute_b32 v11, v209, v7
	s_waitcnt lgkmcnt(0)
	v_add_f32_e32 v7, v7, v11
	ds_bpermute_b32 v11, v210, v7
	s_waitcnt vmcnt(9)
	v_add_f32_e32 v34, 1.0, v80
	v_add_f32_e32 v36, 1.0, v82
	s_waitcnt vmcnt(8)
	v_add_f32_e32 v41, 1.0, v84
	v_add_f32_e32 v42, 1.0, v85
	v_add_f32_e32 v43, 1.0, v86
	v_add_f32_e32 v44, 1.0, v87
	v_add_f32_e32 v35, 1.0, v81
	v_add_f32_e32 v37, 1.0, v83
	s_waitcnt vmcnt(4)
	v_fma_f32 v14, v14, v34, v88
	v_fma_f32 v15, v15, v36, v90
	s_waitcnt vmcnt(3)
	v_fma_f32 v33, v41, v33, v92
	v_fma_f32 v38, v42, v38, v93
	v_fma_f32 v39, v43, v39, v94
	v_fma_f32 v53, v44, v40, v95
	v_fma_f32 v34, v12, v35, v89
	v_fma_f32 v49, v13, v37, v91
	v_cvt_pk_bf16_f32 v12, v33, v38
	v_cvt_pk_bf16_f32 v13, v39, v53
	v_cvt_pk_bf16_f32 v14, v14, v34
	v_cvt_pk_bf16_f32 v15, v15, v49
	global_store_dwordx4 v[60:61], v[12:15], off offset:1024
	s_and_saveexec_b64 s[2:3], vcc
	s_cbranch_execz .LBB0_983
	v_ashrrev_i32_e32 v12, 13, v10
	v_mul_i32_i24_e32 v12, 0x1800, v12
	v_ashrrev_i32_e32 v13, 31, v12
	v_lshl_add_u64 v[38:39], v[12:13], 2, s[16:17]
	v_lshl_add_u64 v[46:47], v[38:39], 0, s[18:19]
	v_lshl_add_u64 v[34:35], v[46:47], 0, v[0:1]
	v_lshl_add_u64 v[48:49], v[38:39], 0, s[20:21]
	global_load_dwordx4 v[80:83], v[34:35], off offset:2048
	global_load_dwordx4 v[84:87], v[34:35], off offset:2064
	global_load_dwordx4 v[12:15], v[34:35], off
	s_nop 0
	global_load_dwordx4 v[34:37], v[34:35], off offset:16
	v_lshl_add_u64 v[42:43], v[48:49], 0, v[0:1]
	global_load_dwordx4 v[88:91], v[42:43], off offset:2048
	global_load_dwordx4 v[92:95], v[42:43], off offset:2064
	global_load_dwordx4 v[38:41], v[42:43], off
	s_nop 0
	global_load_dwordx4 v[42:45], v[42:43], off offset:16
	s_waitcnt lgkmcnt(0)
	v_add_f32_e32 v33, v7, v11
	v_fmamk_f32 v33, v33, 0x3a800000, v16
	v_mul_f32_e32 v50, 0x4b800000, v33
	v_cmp_gt_f32_e32 vcc, s23, v33
	v_ashrrev_i32_e32 v11, 31, v10
	v_mov_b32_e32 v7, v1
	v_cndmask_b32_e32 v33, v33, v50, vcc
	v_rsq_f32_e32 v33, v33
	v_lshlrev_b64 v[50:51], 11, v[10:11]
	v_lshl_add_u64 v[50:51], v[4:5], 0, v[50:51]
	v_lshl_add_u64 v[46:47], v[46:47], 0, v[6:7]
	v_mul_f32_e32 v11, 0x45800000, v33
	v_cndmask_b32_e32 v11, v33, v11, vcc
	v_mul_f32_e32 v17, v11, v17
	v_mul_f32_e32 v24, v11, v24
	v_mul_f32_e32 v27, v11, v27
	v_mul_f32_e32 v28, v11, v28
	v_mul_f32_e32 v29, v11, v29
	v_mul_f32_e32 v30, v11, v30
	v_mul_f32_e32 v31, v11, v31
	v_mul_f32_e32 v32, v11, v32
	v_mul_f32_e32 v23, v11, v23
	v_mul_f32_e32 v22, v11, v22
	v_mul_f32_e32 v21, v11, v21
	v_mul_f32_e32 v20, v11, v20
	v_mul_f32_e32 v19, v11, v19
	s_waitcnt vmcnt(5)
	v_add_f32_e32 v12, 1.0, v12
	v_add_f32_e32 v13, 1.0, v13
	v_add_f32_e32 v14, 1.0, v14
	v_add_f32_e32 v15, 1.0, v15
	s_waitcnt vmcnt(4)
	v_add_f32_e32 v33, 1.0, v34
	v_add_f32_e32 v34, 1.0, v35
	v_add_f32_e32 v35, 1.0, v36
	v_add_f32_e32 v36, 1.0, v37
	s_waitcnt vmcnt(1)
	v_fma_f32 v12, v17, v12, v38
	v_fma_f32 v13, v24, v13, v39
	v_fma_f32 v14, v27, v14, v40
	v_fmac_f32_e32 v41, v28, v15
	s_waitcnt vmcnt(0)
	v_fma_f32 v15, v29, v33, v42
	v_fma_f32 v17, v30, v34, v43
	v_fma_f32 v24, v31, v35, v44
	v_fmac_f32_e32 v45, v32, v36
	v_cvt_pk_bf16_f32 v12, v12, v13
	v_cvt_pk_bf16_f32 v13, v14, v41
	v_cvt_pk_bf16_f32 v14, v15, v17
	v_cvt_pk_bf16_f32 v15, v24, v45
	global_store_dwordx4 v[50:51], v[12:15], off
	s_nop 0
	v_lshl_add_u64 v[36:37], v[48:49], 0, v[6:7]
	s_nop 0
	v_mul_f32_e32 v7, v11, v26
	v_mul_f32_e32 v17, v11, v25
	v_mul_f32_e32 v11, v11, v18
	s_waitcnt vmcnt(8)
	v_add_f32_e32 v12, 1.0, v80
	v_add_f32_e32 v13, 1.0, v81
	v_add_f32_e32 v14, 1.0, v82
	v_add_f32_e32 v15, 1.0, v83
	s_waitcnt vmcnt(7)
	v_add_f32_e32 v18, 1.0, v84
	v_add_f32_e32 v24, 1.0, v85
	v_add_f32_e32 v25, 1.0, v86
	v_add_f32_e32 v26, 1.0, v87
	s_waitcnt vmcnt(4)
	v_fma_f32 v7, v7, v12, v88
	v_fma_f32 v12, v17, v13, v89
	v_fma_f32 v13, v23, v14, v90
	v_fma_f32 v35, v22, v15, v91
	s_waitcnt vmcnt(3)
	v_fma_f32 v14, v21, v18, v92
	v_fma_f32 v15, v20, v24, v93
	v_fma_f32 v17, v19, v25, v94
	v_fma_f32 v39, v11, v26, v95
	v_cvt_pk_bf16_f32 v12, v7, v12
	v_cvt_pk_bf16_f32 v13, v13, v35
	v_cvt_pk_bf16_f32 v14, v14, v15
	v_cvt_pk_bf16_f32 v15, v17, v39
	global_store_dwordx4 v[50:51], v[12:15], off offset:1024
	s_branch .LBB0_983
